# v29 + second k-half fragment ds_reads issued before the first MFMA half (into v200-v231), counted lgkmcnt(8)/(0) waits, in all 7 GEMM K-loops
# speedup vs baseline: 1.0049x; 1.0045x over previous
.LBB0_303:
	s_setprio 3
	s_and_b32 s1, s0, 0x2000
	s_xor_b32 s8, s1, 0x2000
	s_lshl_b32 s101, s8, 1
	s_add_u32 s101, s101, s100
	s_add_u32 m0, s101, 0x0
	s_nop 0
	global_load_lds_dwordx4 v[184:185], off
	s_add_u32 m0, s101, 0x1000
	v_lshl_add_u64 v[184:185], v[184:185], 0, vcc
	global_load_lds_dwordx4 v[186:187], off
	s_add_u32 m0, s101, 0x2000
	v_lshl_add_u64 v[186:187], v[186:187], 0, vcc
	global_load_lds_dwordx4 v[188:189], off
	s_add_u32 m0, s101, 0x3000
	v_lshl_add_u64 v[188:189], v[188:189], 0, vcc
	global_load_lds_dwordx4 v[190:191], off
	s_add_u32 m0, s101, 0x8000
	v_lshl_add_u64 v[190:191], v[190:191], 0, vcc
	global_load_lds_dwordx4 v[192:193], off
	s_add_u32 m0, s101, 0x9000
	v_lshl_add_u64 v[192:193], v[192:193], 0, vcc
	global_load_lds_dwordx4 v[194:195], off
	s_add_u32 m0, s101, 0xa000
	v_lshl_add_u64 v[194:195], v[194:195], 0, vcc
	global_load_lds_dwordx4 v[196:197], off
	s_add_u32 m0, s101, 0xb000
	v_lshl_add_u64 v[196:197], v[196:197], 0, vcc
	global_load_lds_dwordx4 v[198:199], off
	v_lshl_add_u64 v[198:199], v[198:199], 0, vcc
	s_lshl_b32 s1, s1, 1
	v_add_u32_e32 v82, s1, v86
	v_add_u32_e32 v83, s1, v85
	v_add_u32_e32 v95, v82, v93
	ds_read_b128 v[96:99], v95
	ds_read_b128 v[100:103], v95 offset:2048
	ds_read_b128 v[120:123], v95 offset:4096
	ds_read_b128 v[124:127], v95 offset:6144
	v_add_u32_e32 v95, v83, v93
	ds_read_b128 v[128:131], v95 offset:32768
	ds_read_b128 v[132:135], v95 offset:34816
	ds_read_b128 v[136:139], v95 offset:36864
	ds_read_b128 v[140:143], v95 offset:38912
	v_add_u32_e32 v82, v82, v94
	ds_read_b128 v[200:203], v82
	ds_read_b128 v[204:207], v82 offset:2048
	ds_read_b128 v[208:211], v82 offset:4096
	ds_read_b128 v[212:215], v82 offset:6144
	v_add_u32_e32 v82, v83, v94
	ds_read_b128 v[216:219], v82 offset:32768
	ds_read_b128 v[220:223], v82 offset:34816
	ds_read_b128 v[224:227], v82 offset:36864
	ds_read_b128 v[228:231], v82 offset:38912
	s_setprio 1
	s_waitcnt lgkmcnt(8)
	v_mfma_f32_16x16x32_bf16 v[60:63], v[128:131], v[96:99], v[60:63]
	v_mfma_f32_16x16x32_bf16 v[56:59], v[132:135], v[96:99], v[56:59]
	v_mfma_f32_16x16x32_bf16 v[52:55], v[136:139], v[96:99], v[52:55]
	v_mfma_f32_16x16x32_bf16 v[48:51], v[140:143], v[96:99], v[48:51]
	v_mfma_f32_16x16x32_bf16 v[44:47], v[128:131], v[100:103], v[44:47]
	v_mfma_f32_16x16x32_bf16 v[40:43], v[132:135], v[100:103], v[40:43]
	v_mfma_f32_16x16x32_bf16 v[36:39], v[136:139], v[100:103], v[36:39]
	v_mfma_f32_16x16x32_bf16 v[32:35], v[140:143], v[100:103], v[32:35]
	v_mfma_f32_16x16x32_bf16 v[28:31], v[128:131], v[120:123], v[28:31]
	v_mfma_f32_16x16x32_bf16 v[24:27], v[132:135], v[120:123], v[24:27]
	v_mfma_f32_16x16x32_bf16 v[20:23], v[136:139], v[120:123], v[20:23]
	v_mfma_f32_16x16x32_bf16 v[16:19], v[140:143], v[120:123], v[16:19]
	v_mfma_f32_16x16x32_bf16 v[12:15], v[128:131], v[124:127], v[12:15]
	v_mfma_f32_16x16x32_bf16 v[8:11], v[132:135], v[124:127], v[8:11]
	v_mfma_f32_16x16x32_bf16 v[4:7], v[136:139], v[124:127], v[4:7]
	v_mfma_f32_16x16x32_bf16 v[0:3], v[140:143], v[124:127], v[0:3]
	s_waitcnt lgkmcnt(0)
	v_mfma_f32_16x16x32_bf16 v[60:63], v[216:219], v[200:203], v[60:63]
	v_mfma_f32_16x16x32_bf16 v[56:59], v[220:223], v[200:203], v[56:59]
	v_mfma_f32_16x16x32_bf16 v[52:55], v[224:227], v[200:203], v[52:55]
	v_mfma_f32_16x16x32_bf16 v[48:51], v[228:231], v[200:203], v[48:51]
	v_mfma_f32_16x16x32_bf16 v[44:47], v[216:219], v[204:207], v[44:47]
	v_mfma_f32_16x16x32_bf16 v[40:43], v[220:223], v[204:207], v[40:43]
	v_mfma_f32_16x16x32_bf16 v[36:39], v[224:227], v[204:207], v[36:39]
	v_mfma_f32_16x16x32_bf16 v[32:35], v[228:231], v[204:207], v[32:35]
	v_mfma_f32_16x16x32_bf16 v[28:31], v[216:219], v[208:211], v[28:31]
	v_mfma_f32_16x16x32_bf16 v[24:27], v[220:223], v[208:211], v[24:27]
	v_mfma_f32_16x16x32_bf16 v[20:23], v[224:227], v[208:211], v[20:23]
	v_mfma_f32_16x16x32_bf16 v[16:19], v[228:231], v[208:211], v[16:19]
	v_mfma_f32_16x16x32_bf16 v[12:15], v[216:219], v[212:215], v[12:15]
	v_mfma_f32_16x16x32_bf16 v[8:11], v[220:223], v[212:215], v[8:11]
	v_mfma_f32_16x16x32_bf16 v[4:7], v[224:227], v[212:215], v[4:7]
	v_mfma_f32_16x16x32_bf16 v[0:3], v[228:231], v[212:215], v[0:3]
	s_setprio 0
	s_addk_i32 s0, 0x2000
	s_waitcnt vmcnt(0)
	s_add_u32 s20, s20, 0x80
	s_addc_u32 s21, s21, 0
	s_cmpk_lg_i32 s20, 0x780
	s_waitcnt vmcnt(0)
	s_barrier
	s_cbranch_scc1 .LBB0_303
	ds_read_b128 v[78:81], v89 offset:55296
	ds_read_b128 v[96:99], v89 offset:53248
	ds_read_b128 v[100:103], v89 offset:51200
	ds_read_b128 v[120:123], v89 offset:49152
	ds_read_b128 v[124:127], v90 offset:22528
	ds_read_b128 v[128:131], v90 offset:20480
	ds_read_b128 v[132:135], v90 offset:18432
	ds_read_b128 v[136:139], v90 offset:16384
	s_setprio 1
	s_waitcnt lgkmcnt(0)
	v_mfma_f32_16x16x32_bf16 v[60:63], v[120:123], v[136:139], v[60:63]
	v_mfma_f32_16x16x32_bf16 v[56:59], v[100:103], v[136:139], v[56:59]
	v_mfma_f32_16x16x32_bf16 v[52:55], v[96:99], v[136:139], v[52:55]
	v_mfma_f32_16x16x32_bf16 v[48:51], v[78:81], v[136:139], v[48:51]
	v_mfma_f32_16x16x32_bf16 v[44:47], v[120:123], v[132:135], v[44:47]
	v_mfma_f32_16x16x32_bf16 v[40:43], v[100:103], v[132:135], v[40:43]
	v_mfma_f32_16x16x32_bf16 v[36:39], v[96:99], v[132:135], v[36:39]
	v_mfma_f32_16x16x32_bf16 v[32:35], v[78:81], v[132:135], v[32:35]
	v_mfma_f32_16x16x32_bf16 v[28:31], v[120:123], v[128:131], v[28:31]
	v_mfma_f32_16x16x32_bf16 v[24:27], v[100:103], v[128:131], v[24:27]
	v_mfma_f32_16x16x32_bf16 v[20:23], v[96:99], v[128:131], v[20:23]
	v_mfma_f32_16x16x32_bf16 v[16:19], v[78:81], v[128:131], v[16:19]
	v_mfma_f32_16x16x32_bf16 v[12:15], v[120:123], v[124:127], v[12:15]
	v_mfma_f32_16x16x32_bf16 v[8:11], v[100:103], v[124:127], v[8:11]
	v_mfma_f32_16x16x32_bf16 v[4:7], v[96:99], v[124:127], v[4:7]
	v_mfma_f32_16x16x32_bf16 v[0:3], v[78:81], v[124:127], v[0:3]
	s_setprio 0
	ds_read_b128 v[78:81], v91 offset:16384
	ds_read_b128 v[96:99], v91 offset:18432
	ds_read_b128 v[100:103], v91 offset:20480
	ds_read_b128 v[120:123], v91 offset:22528
	ds_read_b128 v[124:127], v92 offset:49152
	ds_read_b128 v[128:131], v92 offset:51200
	ds_read_b128 v[132:135], v92 offset:53248
	ds_read_b128 v[136:139], v92 offset:55296
	s_setprio 1
	s_waitcnt lgkmcnt(3)
	v_mfma_f32_16x16x32_bf16 v[60:63], v[124:127], v[78:81], v[60:63]
	s_waitcnt lgkmcnt(2)
	v_mfma_f32_16x16x32_bf16 v[56:59], v[128:131], v[78:81], v[56:59]
	s_waitcnt lgkmcnt(1)
	v_mfma_f32_16x16x32_bf16 v[52:55], v[132:135], v[78:81], v[52:55]
	s_waitcnt lgkmcnt(0)
	v_mfma_f32_16x16x32_bf16 v[48:51], v[136:139], v[78:81], v[48:51]
	v_mfma_f32_16x16x32_bf16 v[44:47], v[124:127], v[96:99], v[44:47]
	v_mfma_f32_16x16x32_bf16 v[40:43], v[128:131], v[96:99], v[40:43]
	v_mfma_f32_16x16x32_bf16 v[36:39], v[132:135], v[96:99], v[36:39]
	v_mfma_f32_16x16x32_bf16 v[32:35], v[136:139], v[96:99], v[32:35]
	v_mfma_f32_16x16x32_bf16 v[28:31], v[124:127], v[100:103], v[28:31]
	v_mfma_f32_16x16x32_bf16 v[24:27], v[128:131], v[100:103], v[24:27]
	v_mfma_f32_16x16x32_bf16 v[20:23], v[132:135], v[100:103], v[20:23]
	v_mfma_f32_16x16x32_bf16 v[16:19], v[136:139], v[100:103], v[16:19]
	v_mfma_f32_16x16x32_bf16 v[12:15], v[124:127], v[120:123], v[12:15]
	v_mfma_f32_16x16x32_bf16 v[8:11], v[128:131], v[120:123], v[8:11]
	v_mfma_f32_16x16x32_bf16 v[4:7], v[132:135], v[120:123], v[4:7]
	v_mfma_f32_16x16x32_bf16 v[0:3], v[136:139], v[120:123], v[0:3]
	s_setprio 0
	s_waitcnt vmcnt(0)
	s_cmp_lt_i32 s10, 32
	s_mov_b64 s[0:1], -1
	s_barrier
	s_cbranch_scc1 .LBB0_594
	s_cmp_eq_u32 s10, 32
	s_cselect_b64 s[0:1], -1, 0
	s_and_b64 vcc, exec, s[0:1]
	v_mov_b32_e32 v79, v63
	v_mov_b32_e32 v82, v62
	v_mov_b32_e32 v83, v61
	v_mov_b32_e32 v95, v60
	s_cbranch_vccz .LBB0_323
	v_cmp_nlt_f32_e64 s[8:9], |v60|, s33
	s_and_saveexec_b64 s[12:13], s[8:9]
	s_xor_b64 s[8:9], exec, s[12:13]
	s_cbranch_execz .LBB0_308
	v_add_f32_e64 v78, |v60|, |v60|
	v_mul_f32_e32 v79, 0x3fb8aa3b, v78
	v_rndne_f32_e32 v80, v79
	s_mov_b32 s11, 0x3fb8aa3b
	v_sub_f32_e32 v81, v79, v80
	v_fma_f32 v79, v78, s11, -v79
	v_fmac_f32_e32 v79, 0x32a5705f, v78
	v_add_f32_e32 v79, v81, v79
	v_cvt_i32_f32_e32 v80, v80
	v_exp_f32_e32 v79, v79
	s_mov_b32 s11, 0xc2ce8ed0
	v_cmp_ngt_f32_e32 vcc, s11, v78
	s_mov_b32 s11, 0x42b17218
	v_ldexp_f32 v79, v79, v80
	v_cndmask_b32_e32 v79, 0, v79, vcc
	v_cmp_nlt_f32_e32 vcc, s11, v78
	s_nop 1
	v_cndmask_b32_e32 v78, v112, v79, vcc
	v_add_f32_e32 v78, 1.0, v78
	v_rcp_f32_e32 v78, v78
	s_nop 0
	v_fma_f32 v78, v78, -2.0, 1.0

.LBB0_882:
	s_setprio 3
	s_and_b32 s6, s0, 0x2000
	s_xor_b32 s8, s6, 0x2000
	s_lshl_b32 s101, s8, 1
	s_add_u32 s101, s101, s100
	s_add_u32 m0, s101, 0x0
	s_nop 0
	global_load_lds_dwordx4 v[184:185], off
	s_add_u32 m0, s101, 0x1000
	v_lshl_add_u64 v[184:185], v[184:185], 0, vcc
	global_load_lds_dwordx4 v[186:187], off
	s_add_u32 m0, s101, 0x2000
	v_lshl_add_u64 v[186:187], v[186:187], 0, vcc
	global_load_lds_dwordx4 v[188:189], off
	s_add_u32 m0, s101, 0x3000
	v_lshl_add_u64 v[188:189], v[188:189], 0, vcc
	global_load_lds_dwordx4 v[190:191], off
	s_add_u32 m0, s101, 0x8000
	v_lshl_add_u64 v[190:191], v[190:191], 0, vcc
	global_load_lds_dwordx4 v[192:193], off
	s_add_u32 m0, s101, 0x9000
	v_lshl_add_u64 v[192:193], v[192:193], 0, vcc
	global_load_lds_dwordx4 v[194:195], off
	s_add_u32 m0, s101, 0xa000
	v_lshl_add_u64 v[194:195], v[194:195], 0, vcc
	global_load_lds_dwordx4 v[196:197], off
	s_add_u32 m0, s101, 0xb000
	v_lshl_add_u64 v[196:197], v[196:197], 0, vcc
	global_load_lds_dwordx4 v[198:199], off
	v_lshl_add_u64 v[198:199], v[198:199], 0, vcc
	s_lshl_b32 s6, s6, 1
	v_add_u32_e32 v102, s6, v90
	v_add_u32_e32 v103, s6, v71
	v_add_u32_e32 v128, v102, v96
	v_add_u32_e32 v144, v103, v96
	ds_read_b128 v[98:101], v128
	ds_read_b128 v[120:123], v128 offset:2048
	ds_read_b128 v[124:127], v128 offset:4096
	ds_read_b128 v[128:131], v128 offset:6144
	ds_read_b128 v[132:135], v144 offset:32768
	ds_read_b128 v[136:139], v144 offset:34816
	ds_read_b128 v[140:143], v144 offset:36864
	ds_read_b128 v[144:147], v144 offset:38912
	v_add_u32_e32 v102, v102, v97
	ds_read_b128 v[200:203], v102
	ds_read_b128 v[204:207], v102 offset:2048
	ds_read_b128 v[208:211], v102 offset:4096
	ds_read_b128 v[212:215], v102 offset:6144
	v_add_u32_e32 v102, v103, v97
	ds_read_b128 v[216:219], v102 offset:32768
	ds_read_b128 v[220:223], v102 offset:34816
	ds_read_b128 v[224:227], v102 offset:36864
	ds_read_b128 v[228:231], v102 offset:38912
	s_setprio 1
	s_waitcnt lgkmcnt(8)
	v_mfma_f32_16x16x32_bf16 v[60:63], v[132:135], v[98:101], v[60:63]
	v_mfma_f32_16x16x32_bf16 v[56:59], v[136:139], v[98:101], v[56:59]
	v_mfma_f32_16x16x32_bf16 v[52:55], v[140:143], v[98:101], v[52:55]
	v_mfma_f32_16x16x32_bf16 v[48:51], v[144:147], v[98:101], v[48:51]
	v_mfma_f32_16x16x32_bf16 v[44:47], v[132:135], v[120:123], v[44:47]
	v_mfma_f32_16x16x32_bf16 v[40:43], v[136:139], v[120:123], v[40:43]
	v_mfma_f32_16x16x32_bf16 v[36:39], v[140:143], v[120:123], v[36:39]
	v_mfma_f32_16x16x32_bf16 v[32:35], v[144:147], v[120:123], v[32:35]
	v_mfma_f32_16x16x32_bf16 v[28:31], v[132:135], v[124:127], v[28:31]
	v_mfma_f32_16x16x32_bf16 v[24:27], v[136:139], v[124:127], v[24:27]
	v_mfma_f32_16x16x32_bf16 v[20:23], v[140:143], v[124:127], v[20:23]
	v_mfma_f32_16x16x32_bf16 v[16:19], v[144:147], v[124:127], v[16:19]
	v_mfma_f32_16x16x32_bf16 v[12:15], v[132:135], v[128:131], v[12:15]
	v_mfma_f32_16x16x32_bf16 v[8:11], v[136:139], v[128:131], v[8:11]
	v_mfma_f32_16x16x32_bf16 v[4:7], v[140:143], v[128:131], v[4:7]
	v_mfma_f32_16x16x32_bf16 v[0:3], v[144:147], v[128:131], v[0:3]
	s_waitcnt lgkmcnt(0)
	v_mfma_f32_16x16x32_bf16 v[60:63], v[216:219], v[200:203], v[60:63]
	v_mfma_f32_16x16x32_bf16 v[56:59], v[220:223], v[200:203], v[56:59]
	v_mfma_f32_16x16x32_bf16 v[52:55], v[224:227], v[200:203], v[52:55]
	v_mfma_f32_16x16x32_bf16 v[48:51], v[228:231], v[200:203], v[48:51]
	v_mfma_f32_16x16x32_bf16 v[44:47], v[216:219], v[204:207], v[44:47]
	v_mfma_f32_16x16x32_bf16 v[40:43], v[220:223], v[204:207], v[40:43]
	v_mfma_f32_16x16x32_bf16 v[36:39], v[224:227], v[204:207], v[36:39]
	v_mfma_f32_16x16x32_bf16 v[32:35], v[228:231], v[204:207], v[32:35]
	v_mfma_f32_16x16x32_bf16 v[28:31], v[216:219], v[208:211], v[28:31]
	v_mfma_f32_16x16x32_bf16 v[24:27], v[220:223], v[208:211], v[24:27]
	v_mfma_f32_16x16x32_bf16 v[20:23], v[224:227], v[208:211], v[20:23]
	v_mfma_f32_16x16x32_bf16 v[16:19], v[228:231], v[208:211], v[16:19]
	v_mfma_f32_16x16x32_bf16 v[12:15], v[216:219], v[212:215], v[12:15]
	v_mfma_f32_16x16x32_bf16 v[8:11], v[220:223], v[212:215], v[8:11]
	v_mfma_f32_16x16x32_bf16 v[4:7], v[224:227], v[212:215], v[4:7]
	v_mfma_f32_16x16x32_bf16 v[0:3], v[228:231], v[212:215], v[0:3]
	s_setprio 0
	s_waitcnt vmcnt(0)
	s_add_u32 s36, s36, 0x80
	s_addc_u32 s37, s37, 0
	s_addk_i32 s0, 0x2000
	s_cmpk_lg_i32 s36, 0x780
	s_waitcnt vmcnt(0)
	s_barrier
	s_cbranch_scc1 .LBB0_882
	ds_read_b128 v[86:89], v92 offset:16384
	ds_read_b128 v[98:101], v92 offset:18432
	ds_read_b128 v[120:123], v92 offset:20480
	ds_read_b128 v[124:127], v92 offset:22528
	ds_read_b128 v[128:131], v93 offset:49152
	ds_read_b128 v[132:135], v93 offset:51200
	ds_read_b128 v[136:139], v93 offset:53248
	ds_read_b128 v[140:143], v93 offset:55296
	s_setprio 1
	s_waitcnt lgkmcnt(3)
	v_mfma_f32_16x16x32_bf16 v[60:63], v[128:131], v[86:89], v[60:63]
	s_waitcnt lgkmcnt(2)
	v_mfma_f32_16x16x32_bf16 v[56:59], v[132:135], v[86:89], v[56:59]
	s_waitcnt lgkmcnt(1)
	v_mfma_f32_16x16x32_bf16 v[52:55], v[136:139], v[86:89], v[52:55]
	s_waitcnt lgkmcnt(0)
	v_mfma_f32_16x16x32_bf16 v[48:51], v[140:143], v[86:89], v[48:51]
	v_mfma_f32_16x16x32_bf16 v[40:43], v[132:135], v[98:101], v[40:43]
	v_mfma_f32_16x16x32_bf16 v[36:39], v[136:139], v[98:101], v[36:39]
	v_mfma_f32_16x16x32_bf16 v[32:35], v[140:143], v[98:101], v[32:35]
	v_mfma_f32_16x16x32_bf16 v[20:23], v[136:139], v[120:123], v[20:23]
	v_mfma_f32_16x16x32_bf16 v[16:19], v[140:143], v[120:123], v[16:19]
	v_mfma_f32_16x16x32_bf16 v[0:3], v[140:143], v[124:127], v[0:3]
	v_mfma_f32_16x16x32_bf16 v[86:89], v[128:131], v[98:101], v[44:47]
	v_mfma_f32_16x16x32_bf16 v[98:101], v[128:131], v[120:123], v[28:31]
	v_mfma_f32_16x16x32_bf16 v[144:147], v[132:135], v[120:123], v[24:27]
	v_mfma_f32_16x16x32_bf16 v[120:123], v[128:131], v[124:127], v[12:15]
	v_mfma_f32_16x16x32_bf16 v[128:131], v[132:135], v[124:127], v[8:11]
	v_mfma_f32_16x16x32_bf16 v[132:135], v[136:139], v[124:127], v[4:7]
	s_setprio 0
	s_nop 1
	ds_read_b128 v[4:7], v94 offset:16384
	ds_read_b128 v[8:11], v94 offset:18432
	ds_read_b128 v[124:127], v94 offset:20480
	ds_read_b128 v[136:139], v94 offset:22528
	ds_read_b128 v[140:143], v95 offset:49152
	ds_read_b128 v[148:151], v95 offset:51200
	ds_read_b128 v[152:155], v95 offset:53248
	ds_read_b128 v[156:159], v95 offset:55296
	s_setprio 1
	s_waitcnt lgkmcnt(3)
	v_mfma_f32_16x16x32_bf16 v[60:63], v[140:143], v[4:7], v[60:63]
	s_waitcnt lgkmcnt(2)
	v_mfma_f32_16x16x32_bf16 v[44:47], v[148:151], v[4:7], v[56:59]
	s_waitcnt lgkmcnt(1)
	v_mfma_f32_16x16x32_bf16 v[28:31], v[152:155], v[4:7], v[52:55]
	s_waitcnt lgkmcnt(0)
	v_mfma_f32_16x16x32_bf16 v[12:15], v[156:159], v[4:7], v[48:51]
	v_mfma_f32_16x16x32_bf16 v[56:59], v[140:143], v[8:11], v[86:89]
	v_mfma_f32_16x16x32_bf16 v[40:43], v[148:151], v[8:11], v[40:43]
	v_mfma_f32_16x16x32_bf16 v[24:27], v[152:155], v[8:11], v[36:39]
	v_mfma_f32_16x16x32_bf16 v[8:11], v[156:159], v[8:11], v[32:35]
	v_mfma_f32_16x16x32_bf16 v[52:55], v[140:143], v[124:127], v[98:101]
	v_mfma_f32_16x16x32_bf16 v[36:39], v[148:151], v[124:127], v[144:147]
	v_mfma_f32_16x16x32_bf16 v[20:23], v[152:155], v[124:127], v[20:23]
	v_mfma_f32_16x16x32_bf16 v[4:7], v[156:159], v[124:127], v[16:19]
	v_mfma_f32_16x16x32_bf16 v[48:51], v[140:143], v[136:139], v[120:123]
	v_mfma_f32_16x16x32_bf16 v[32:35], v[148:151], v[136:139], v[128:131]
	v_mfma_f32_16x16x32_bf16 v[16:19], v[152:155], v[136:139], v[132:135]
	v_mfma_f32_16x16x32_bf16 v[0:3], v[156:159], v[136:139], v[0:3]
	s_setprio 0
	s_waitcnt vmcnt(0)
	s_cmpk_gt_i32 s1, 0x7f
	s_barrier
	s_cbranch_scc0 .LBB0_885
	s_add_i32 s0, s24, 0xffffc000
	s_lshr_b32 s0, s0, 8
	v_readlane_b32 s6, v180, 24
	s_add_i32 s6, s0, s6
	s_and_b32 s10, s24, 0x80
	s_lshl_b64 s[8:9], s[6:7], 8
	v_readlane_b32 s36, v182, 19
	s_or_b32 s8, s8, s10
	s_mov_b64 s[10:11], 0
	v_readlane_b32 s37, v182, 20
	s_branch .LBB0_886

.LBB0_895:
	s_setprio 3
	s_and_b32 s0, s10, 0x2000
	s_xor_b32 s1, s0, 0x2000
	s_lshl_b32 s101, s1, 1
	s_add_u32 s101, s101, s100
	s_add_u32 m0, s101, 0x0
	s_nop 0
	global_load_lds_dwordx4 v[184:185], off
	s_add_u32 m0, s101, 0x1000
	v_lshl_add_u64 v[184:185], v[184:185], 0, vcc
	global_load_lds_dwordx4 v[186:187], off
	s_add_u32 m0, s101, 0x2000
	v_lshl_add_u64 v[186:187], v[186:187], 0, vcc
	global_load_lds_dwordx4 v[188:189], off
	s_add_u32 m0, s101, 0x3000
	v_lshl_add_u64 v[188:189], v[188:189], 0, vcc
	global_load_lds_dwordx4 v[190:191], off
	s_add_u32 m0, s101, 0x8000
	v_lshl_add_u64 v[190:191], v[190:191], 0, vcc
	global_load_lds_dwordx4 v[192:193], off
	s_add_u32 m0, s101, 0x9000
	v_lshl_add_u64 v[192:193], v[192:193], 0, vcc
	global_load_lds_dwordx4 v[194:195], off
	s_add_u32 m0, s101, 0xa000
	v_lshl_add_u64 v[194:195], v[194:195], 0, vcc
	global_load_lds_dwordx4 v[196:197], off
	s_add_u32 m0, s101, 0xb000
	v_lshl_add_u64 v[196:197], v[196:197], 0, vcc
	global_load_lds_dwordx4 v[198:199], off
	v_lshl_add_u64 v[198:199], v[198:199], 0, vcc
	s_lshl_b32 s0, s0, 1
	v_add_u32_e32 v68, s0, v120
	v_add_u32_e32 v102, s0, v121
	v_add_u32_e32 v98, v68, v133
	v_add_u32_e32 v103, v102, v133
	ds_read_b128 v[86:89], v98
	ds_read_b128 v[90:93], v98 offset:2048
	ds_read_b128 v[94:97], v98 offset:4096
	ds_read_b128 v[98:101], v98 offset:6144
	ds_read_b128 v[144:147], v103 offset:32768
	ds_read_b128 v[148:151], v103 offset:34816
	ds_read_b128 v[152:155], v103 offset:36864
	ds_read_b128 v[156:159], v103 offset:38912
	v_add_u32_e32 v68, v68, v134
	ds_read_b128 v[200:203], v68
	ds_read_b128 v[204:207], v68 offset:2048
	ds_read_b128 v[208:211], v68 offset:4096
	ds_read_b128 v[212:215], v68 offset:6144
	v_add_u32_e32 v68, v102, v134
	ds_read_b128 v[216:219], v68 offset:32768
	ds_read_b128 v[220:223], v68 offset:34816
	ds_read_b128 v[224:227], v68 offset:36864
	ds_read_b128 v[228:231], v68 offset:38912
	s_setprio 1
	s_waitcnt lgkmcnt(8)
	v_mfma_f32_16x16x32_bf16 v[60:63], v[86:89], v[144:147], v[60:63]
	v_mfma_f32_16x16x32_bf16 v[56:59], v[86:89], v[148:151], v[56:59]
	v_mfma_f32_16x16x32_bf16 v[52:55], v[86:89], v[152:155], v[52:55]
	v_mfma_f32_16x16x32_bf16 v[48:51], v[86:89], v[156:159], v[48:51]
	v_mfma_f32_16x16x32_bf16 v[44:47], v[90:93], v[144:147], v[44:47]
	v_mfma_f32_16x16x32_bf16 v[40:43], v[90:93], v[148:151], v[40:43]
	v_mfma_f32_16x16x32_bf16 v[36:39], v[90:93], v[152:155], v[36:39]
	v_mfma_f32_16x16x32_bf16 v[32:35], v[90:93], v[156:159], v[32:35]
	v_mfma_f32_16x16x32_bf16 v[28:31], v[94:97], v[144:147], v[28:31]
	v_mfma_f32_16x16x32_bf16 v[24:27], v[94:97], v[148:151], v[24:27]
	v_mfma_f32_16x16x32_bf16 v[20:23], v[94:97], v[152:155], v[20:23]
	v_mfma_f32_16x16x32_bf16 v[16:19], v[94:97], v[156:159], v[16:19]
	v_mfma_f32_16x16x32_bf16 v[12:15], v[98:101], v[144:147], v[12:15]
	v_mfma_f32_16x16x32_bf16 v[8:11], v[98:101], v[148:151], v[8:11]
	v_mfma_f32_16x16x32_bf16 v[4:7], v[98:101], v[152:155], v[4:7]
	v_mfma_f32_16x16x32_bf16 v[0:3], v[98:101], v[156:159], v[0:3]
	s_waitcnt lgkmcnt(0)
	v_mfma_f32_16x16x32_bf16 v[60:63], v[200:203], v[216:219], v[60:63]
	v_mfma_f32_16x16x32_bf16 v[56:59], v[200:203], v[220:223], v[56:59]
	v_mfma_f32_16x16x32_bf16 v[52:55], v[200:203], v[224:227], v[52:55]
	v_mfma_f32_16x16x32_bf16 v[48:51], v[200:203], v[228:231], v[48:51]
	v_mfma_f32_16x16x32_bf16 v[44:47], v[204:207], v[216:219], v[44:47]
	v_mfma_f32_16x16x32_bf16 v[40:43], v[204:207], v[220:223], v[40:43]
	v_mfma_f32_16x16x32_bf16 v[36:39], v[204:207], v[224:227], v[36:39]
	v_mfma_f32_16x16x32_bf16 v[32:35], v[204:207], v[228:231], v[32:35]
	v_mfma_f32_16x16x32_bf16 v[28:31], v[208:211], v[216:219], v[28:31]
	v_mfma_f32_16x16x32_bf16 v[24:27], v[208:211], v[220:223], v[24:27]
	v_mfma_f32_16x16x32_bf16 v[20:23], v[208:211], v[224:227], v[20:23]
	v_mfma_f32_16x16x32_bf16 v[16:19], v[208:211], v[228:231], v[16:19]
	v_mfma_f32_16x16x32_bf16 v[12:15], v[212:215], v[216:219], v[12:15]
	v_mfma_f32_16x16x32_bf16 v[8:11], v[212:215], v[220:223], v[8:11]
	v_mfma_f32_16x16x32_bf16 v[4:7], v[212:215], v[224:227], v[4:7]
	v_mfma_f32_16x16x32_bf16 v[0:3], v[212:215], v[228:231], v[0:3]
	s_setprio 0
	s_addk_i32 s10, 0x2000
	s_waitcnt vmcnt(0)
	s_add_u32 s36, s36, 0x80
	s_addc_u32 s37, s37, 0
	s_cmpk_lg_i32 s36, 0x780
	s_waitcnt vmcnt(0)
	s_barrier
	s_cbranch_scc1 .LBB0_895
	ds_read_b128 v[82:85], v122 offset:55296
	ds_read_b128 v[86:89], v122 offset:53248
	ds_read_b128 v[90:93], v122 offset:51200
	ds_read_b128 v[94:97], v122 offset:49152
	ds_read_b128 v[98:101], v123 offset:22528
	ds_read_b128 v[144:147], v123 offset:20480
	ds_read_b128 v[148:151], v123 offset:18432
	ds_read_b128 v[152:155], v123 offset:16384
	s_setprio 1
	s_waitcnt lgkmcnt(0)
	v_mfma_f32_16x16x32_bf16 v[60:63], v[152:155], v[94:97], v[60:63]
	v_mfma_f32_16x16x32_bf16 v[52:55], v[152:155], v[86:89], v[52:55]
	v_mfma_f32_16x16x32_bf16 v[48:51], v[152:155], v[82:85], v[48:51]
	v_mfma_f32_16x16x32_bf16 v[44:47], v[148:151], v[94:97], v[44:47]
	v_mfma_f32_16x16x32_bf16 v[40:43], v[148:151], v[90:93], v[40:43]
	v_mfma_f32_16x16x32_bf16 v[36:39], v[148:151], v[86:89], v[36:39]
	v_mfma_f32_16x16x32_bf16 v[32:35], v[148:151], v[82:85], v[32:35]
	v_mfma_f32_16x16x32_bf16 v[4:7], v[98:101], v[86:89], v[4:7]
	v_mfma_f32_16x16x32_bf16 v[156:159], v[152:155], v[90:93], v[56:59]
	v_mfma_f32_16x16x32_bf16 v[148:151], v[144:147], v[94:97], v[28:31]
	v_mfma_f32_16x16x32_bf16 v[152:155], v[144:147], v[90:93], v[24:27]
	v_mfma_f32_16x16x32_bf16 v[160:163], v[144:147], v[86:89], v[20:23]
	v_mfma_f32_16x16x32_bf16 v[144:147], v[144:147], v[82:85], v[16:19]
	v_mfma_f32_16x16x32_bf16 v[94:97], v[98:101], v[94:97], v[12:15]
	v_mfma_f32_16x16x32_bf16 v[90:93], v[98:101], v[90:93], v[8:11]
	v_mfma_f32_16x16x32_bf16 v[82:85], v[98:101], v[82:85], v[0:3]
	s_setprio 0
	s_nop 1
	ds_read_b128 v[0:3], v124 offset:16384
	ds_read_b128 v[8:11], v124 offset:18432
	ds_read_b128 v[12:15], v124 offset:20480
	ds_read_b128 v[86:89], v124 offset:22528
	ds_read_b128 v[98:101], v125 offset:49152
	ds_read_b128 v[164:167], v125 offset:51200
	ds_read_b128 v[168:171], v125 offset:53248
	ds_read_b128 v[172:175], v125 offset:55296
	s_setprio 1
	s_waitcnt lgkmcnt(3)
	v_mfma_f32_16x16x32_bf16 v[56:59], v[0:3], v[98:101], v[60:63]
	s_waitcnt lgkmcnt(2)
	v_mfma_f32_16x16x32_bf16 v[60:63], v[0:3], v[164:167], v[156:159]
	s_waitcnt lgkmcnt(1)
	v_mfma_f32_16x16x32_bf16 v[24:27], v[0:3], v[168:171], v[52:55]
	s_waitcnt lgkmcnt(0)
	v_mfma_f32_16x16x32_bf16 v[28:31], v[0:3], v[172:175], v[48:51]
	v_mfma_f32_16x16x32_bf16 v[52:55], v[8:11], v[98:101], v[44:47]
	v_mfma_f32_16x16x32_bf16 v[48:51], v[8:11], v[164:167], v[40:43]
	v_mfma_f32_16x16x32_bf16 v[16:19], v[8:11], v[168:171], v[36:39]
	v_mfma_f32_16x16x32_bf16 v[20:23], v[8:11], v[172:175], v[32:35]
	v_mfma_f32_16x16x32_bf16 v[40:43], v[12:15], v[98:101], v[148:151]
	v_mfma_f32_16x16x32_bf16 v[44:47], v[12:15], v[164:167], v[152:155]
	v_mfma_f32_16x16x32_bf16 v[8:11], v[12:15], v[168:171], v[160:163]
	v_mfma_f32_16x16x32_bf16 v[12:15], v[12:15], v[172:175], v[144:147]
	v_mfma_f32_16x16x32_bf16 v[32:35], v[86:89], v[98:101], v[94:97]
	v_mfma_f32_16x16x32_bf16 v[36:39], v[86:89], v[164:167], v[90:93]
	v_mfma_f32_16x16x32_bf16 v[0:3], v[86:89], v[168:171], v[4:7]
	v_mfma_f32_16x16x32_bf16 v[4:7], v[86:89], v[172:175], v[82:85]
	s_setprio 0
	s_waitcnt vmcnt(0)
	s_cmpk_lt_i32 s9, 0x80
	s_cselect_b64 s[42:43], -1, 0
	s_cmpk_gt_i32 s9, 0x7f
	s_mov_b64 s[0:1], -1
	s_barrier
	s_cbranch_scc0 .LBB0_904
	s_and_b32 s10, s20, 0x80
	s_cbranch_execz .LBB0_905

.LBB0_1239:
	s_setprio 3
	s_and_b32 s9, s8, 0x2000
	s_xor_b32 s18, s9, 0x2000
	s_lshl_b32 s101, s18, 1
	s_add_u32 s101, s101, s100
	s_add_u32 m0, s101, 0x0
	s_nop 0
	global_load_lds_dwordx4 v[184:185], off
	s_add_u32 m0, s101, 0x1000
	v_lshl_add_u64 v[184:185], v[184:185], 0, vcc
	global_load_lds_dwordx4 v[186:187], off
	s_add_u32 m0, s101, 0x2000
	v_lshl_add_u64 v[186:187], v[186:187], 0, vcc
	global_load_lds_dwordx4 v[188:189], off
	s_add_u32 m0, s101, 0x3000
	v_lshl_add_u64 v[188:189], v[188:189], 0, vcc
	global_load_lds_dwordx4 v[190:191], off
	s_add_u32 m0, s101, 0x8000
	v_lshl_add_u64 v[190:191], v[190:191], 0, vcc
	global_load_lds_dwordx4 v[192:193], off
	s_add_u32 m0, s101, 0x9000
	v_lshl_add_u64 v[192:193], v[192:193], 0, vcc
	global_load_lds_dwordx4 v[194:195], off
	s_add_u32 m0, s101, 0xa000
	v_lshl_add_u64 v[194:195], v[194:195], 0, vcc
	global_load_lds_dwordx4 v[196:197], off
	s_add_u32 m0, s101, 0xb000
	v_lshl_add_u64 v[196:197], v[196:197], 0, vcc
	global_load_lds_dwordx4 v[198:199], off
	v_lshl_add_u64 v[198:199], v[198:199], 0, vcc
	s_lshl_b32 s9, s9, 1
	v_add_u32_e32 v136, s9, v84
	v_add_u32_e32 v137, s9, v83
	v_add_u32_e32 v100, v136, v86
	v_add_u32_e32 v132, v137, v86
	ds_read_b128 v[88:91], v100
	ds_read_b128 v[92:95], v100 offset:2048
	ds_read_b128 v[96:99], v100 offset:4096
	ds_read_b128 v[100:103], v100 offset:6144
	ds_read_b128 v[120:123], v132 offset:32768
	ds_read_b128 v[124:127], v132 offset:34816
	ds_read_b128 v[128:131], v132 offset:36864
	ds_read_b128 v[132:135], v132 offset:38912
	v_add_u32_e32 v232, v136, v87
	v_add_u32_e32 v233, v137, v87
	ds_read_b128 v[200:203], v232
	ds_read_b128 v[204:207], v232 offset:2048
	ds_read_b128 v[208:211], v232 offset:4096
	ds_read_b128 v[212:215], v232 offset:6144
	ds_read_b128 v[216:219], v233 offset:32768
	ds_read_b128 v[220:223], v233 offset:34816
	ds_read_b128 v[224:227], v233 offset:36864
	ds_read_b128 v[228:231], v233 offset:38912
	s_setprio 1
	s_waitcnt lgkmcnt(8)
	v_mfma_f32_16x16x32_bf16 v[60:63], v[120:123], v[88:91], v[60:63]
	v_mfma_f32_16x16x32_bf16 v[56:59], v[124:127], v[88:91], v[56:59]
	v_mfma_f32_16x16x32_bf16 v[52:55], v[128:131], v[88:91], v[52:55]
	v_mfma_f32_16x16x32_bf16 v[48:51], v[132:135], v[88:91], v[48:51]
	v_mfma_f32_16x16x32_bf16 v[44:47], v[120:123], v[92:95], v[44:47]
	v_mfma_f32_16x16x32_bf16 v[40:43], v[124:127], v[92:95], v[40:43]
	v_mfma_f32_16x16x32_bf16 v[36:39], v[128:131], v[92:95], v[36:39]
	v_mfma_f32_16x16x32_bf16 v[32:35], v[132:135], v[92:95], v[32:35]
	v_mfma_f32_16x16x32_bf16 v[28:31], v[120:123], v[96:99], v[28:31]
	v_mfma_f32_16x16x32_bf16 v[24:27], v[124:127], v[96:99], v[24:27]
	v_mfma_f32_16x16x32_bf16 v[20:23], v[128:131], v[96:99], v[20:23]
	v_mfma_f32_16x16x32_bf16 v[16:19], v[132:135], v[96:99], v[16:19]
	v_mfma_f32_16x16x32_bf16 v[12:15], v[120:123], v[100:103], v[12:15]
	v_mfma_f32_16x16x32_bf16 v[8:11], v[124:127], v[100:103], v[8:11]
	v_mfma_f32_16x16x32_bf16 v[4:7], v[128:131], v[100:103], v[4:7]
	v_mfma_f32_16x16x32_bf16 v[0:3], v[132:135], v[100:103], v[0:3]
	s_waitcnt lgkmcnt(0)
	v_mfma_f32_16x16x32_bf16 v[60:63], v[216:219], v[200:203], v[60:63]
	v_mfma_f32_16x16x32_bf16 v[56:59], v[220:223], v[200:203], v[56:59]
	v_mfma_f32_16x16x32_bf16 v[52:55], v[224:227], v[200:203], v[52:55]
	v_mfma_f32_16x16x32_bf16 v[48:51], v[228:231], v[200:203], v[48:51]
	v_mfma_f32_16x16x32_bf16 v[44:47], v[216:219], v[204:207], v[44:47]
	v_mfma_f32_16x16x32_bf16 v[40:43], v[220:223], v[204:207], v[40:43]
	v_mfma_f32_16x16x32_bf16 v[36:39], v[224:227], v[204:207], v[36:39]
	v_mfma_f32_16x16x32_bf16 v[32:35], v[228:231], v[204:207], v[32:35]
	v_mfma_f32_16x16x32_bf16 v[28:31], v[216:219], v[208:211], v[28:31]
	v_mfma_f32_16x16x32_bf16 v[24:27], v[220:223], v[208:211], v[24:27]
	v_mfma_f32_16x16x32_bf16 v[20:23], v[224:227], v[208:211], v[20:23]
	v_mfma_f32_16x16x32_bf16 v[16:19], v[228:231], v[208:211], v[16:19]
	v_mfma_f32_16x16x32_bf16 v[12:15], v[216:219], v[212:215], v[12:15]
	v_mfma_f32_16x16x32_bf16 v[8:11], v[220:223], v[212:215], v[8:11]
	v_mfma_f32_16x16x32_bf16 v[4:7], v[224:227], v[212:215], v[4:7]
	v_mfma_f32_16x16x32_bf16 v[0:3], v[228:231], v[212:215], v[0:3]
	s_setprio 0
	s_waitcnt vmcnt(0)
	s_add_u32 s20, s20, 0x80
	s_addc_u32 s21, s21, 0
	s_addk_i32 s8, 0x2000
	s_cmp_lg_u32 s1, s20
	s_waitcnt vmcnt(0)
	s_barrier
	s_cbranch_scc1 .LBB0_1239
	s_lshl_b32 s1, s36, 14
	s_addk_i32 s1, 0x4000
	s_and_b32 s1, s1, 0x4000
	v_add_u32_e32 v132, s1, v84
	v_add_u32_e32 v133, s1, v83
	v_add_u32_e32 v96, v132, v86
	v_add_u32_e32 v128, v133, v86
	ds_read_b128 v[78:81], v96
	ds_read_b128 v[88:91], v96 offset:2048
	ds_read_b128 v[92:95], v96 offset:4096
	ds_read_b128 v[96:99], v96 offset:6144
	ds_read_b128 v[100:103], v128 offset:32768
	ds_read_b128 v[120:123], v128 offset:34816
	ds_read_b128 v[124:127], v128 offset:36864
	ds_read_b128 v[128:131], v128 offset:38912
	s_setprio 1
	s_waitcnt lgkmcnt(3)
	v_mfma_f32_16x16x32_bf16 v[60:63], v[100:103], v[78:81], v[60:63]
	s_waitcnt lgkmcnt(2)
	v_mfma_f32_16x16x32_bf16 v[56:59], v[120:123], v[78:81], v[56:59]
	s_waitcnt lgkmcnt(1)
	v_mfma_f32_16x16x32_bf16 v[52:55], v[124:127], v[78:81], v[52:55]
	s_waitcnt lgkmcnt(0)
	v_mfma_f32_16x16x32_bf16 v[48:51], v[128:131], v[78:81], v[48:51]
	v_mfma_f32_16x16x32_bf16 v[44:47], v[100:103], v[88:91], v[44:47]
	v_mfma_f32_16x16x32_bf16 v[40:43], v[120:123], v[88:91], v[40:43]
	v_mfma_f32_16x16x32_bf16 v[36:39], v[124:127], v[88:91], v[36:39]
	v_mfma_f32_16x16x32_bf16 v[32:35], v[128:131], v[88:91], v[32:35]
	v_mfma_f32_16x16x32_bf16 v[28:31], v[100:103], v[92:95], v[28:31]
	v_mfma_f32_16x16x32_bf16 v[24:27], v[120:123], v[92:95], v[24:27]
	v_mfma_f32_16x16x32_bf16 v[20:23], v[124:127], v[92:95], v[20:23]
	v_mfma_f32_16x16x32_bf16 v[16:19], v[128:131], v[92:95], v[16:19]
	v_mfma_f32_16x16x32_bf16 v[12:15], v[100:103], v[96:99], v[12:15]
	v_mfma_f32_16x16x32_bf16 v[8:11], v[120:123], v[96:99], v[8:11]
	v_mfma_f32_16x16x32_bf16 v[4:7], v[124:127], v[96:99], v[4:7]
	v_mfma_f32_16x16x32_bf16 v[0:3], v[128:131], v[96:99], v[0:3]
	s_setprio 0
	v_add_u32_e32 v96, v132, v87
	v_add_u32_e32 v128, v133, v87
	ds_read_b128 v[78:81], v96
	ds_read_b128 v[88:91], v96 offset:2048
	ds_read_b128 v[92:95], v96 offset:4096
	ds_read_b128 v[96:99], v96 offset:6144
	ds_read_b128 v[100:103], v128 offset:32768
	ds_read_b128 v[120:123], v128 offset:34816
	ds_read_b128 v[124:127], v128 offset:36864
	ds_read_b128 v[128:131], v128 offset:38912
	s_setprio 1
	s_waitcnt lgkmcnt(3)
	v_mfma_f32_16x16x32_bf16 v[60:63], v[100:103], v[78:81], v[60:63]
	s_waitcnt lgkmcnt(2)
	v_mfma_f32_16x16x32_bf16 v[56:59], v[120:123], v[78:81], v[56:59]
	s_waitcnt lgkmcnt(1)
	v_mfma_f32_16x16x32_bf16 v[52:55], v[124:127], v[78:81], v[52:55]
	s_waitcnt lgkmcnt(0)
	v_mfma_f32_16x16x32_bf16 v[48:51], v[128:131], v[78:81], v[48:51]
	v_mfma_f32_16x16x32_bf16 v[44:47], v[100:103], v[88:91], v[44:47]
	v_mfma_f32_16x16x32_bf16 v[40:43], v[120:123], v[88:91], v[40:43]
	v_mfma_f32_16x16x32_bf16 v[36:39], v[124:127], v[88:91], v[36:39]
	v_mfma_f32_16x16x32_bf16 v[32:35], v[128:131], v[88:91], v[32:35]
	v_mfma_f32_16x16x32_bf16 v[28:31], v[100:103], v[92:95], v[28:31]
	v_mfma_f32_16x16x32_bf16 v[24:27], v[120:123], v[92:95], v[24:27]
	v_mfma_f32_16x16x32_bf16 v[20:23], v[124:127], v[92:95], v[20:23]
	v_mfma_f32_16x16x32_bf16 v[16:19], v[128:131], v[92:95], v[16:19]
	v_mfma_f32_16x16x32_bf16 v[12:15], v[100:103], v[96:99], v[12:15]
	v_mfma_f32_16x16x32_bf16 v[8:11], v[120:123], v[96:99], v[8:11]
	v_mfma_f32_16x16x32_bf16 v[4:7], v[124:127], v[96:99], v[4:7]
	v_mfma_f32_16x16x32_bf16 v[0:3], v[128:131], v[96:99], v[0:3]
	s_setprio 0
	s_lshl_b32 s1, s25, 3
	s_lshl_b32 s8, s11, 1
	s_or_b32 s1, s8, s1
	s_or_b32 s1, s1, s13
	s_lshl_b32 s1, s1, 4
	s_or_b32 s8, s1, s24
	s_ashr_i32 s9, s8, 31
	s_lshl_b64 s[8:9], s[8:9], 18
	s_add_u32 s8, s52, s8
	v_add_lshl_u32 v78, s10, v71, 8
	s_addc_u32 s9, s53, s9
	v_or_b32_e32 v80, s0, v85
	v_ashrrev_i32_e32 v79, 31, v78
	v_lshl_add_u64 v[78:79], v[78:79], 1, s[8:9]
	v_cvt_pk_bf16_f32 v60, v60, v61
	v_cvt_pk_bf16_f32 v61, v62, v63
	v_lshlrev_b32_e32 v62, 1, v80
	v_mov_b32_e32 v63, v69
	v_lshl_add_u64 v[80:81], v[78:79], 0, v[62:63]
	v_cvt_pk_bf16_f32 v48, v48, v49
	v_cvt_pk_bf16_f32 v49, v50, v51
	s_mov_b64 s[0:1], 0x2000
	s_waitcnt vmcnt(0)
	s_barrier
	global_store_dwordx2 v[80:81], v[48:49], off offset:96
	v_lshl_add_u64 v[48:49], v[78:79], 0, s[0:1]
	v_cvt_pk_bf16_f32 v44, v44, v45
	v_cvt_pk_bf16_f32 v45, v46, v47
	v_lshl_add_u64 v[46:47], v[48:49], 0, v[62:63]
	v_cvt_pk_bf16_f32 v40, v40, v41
	v_cvt_pk_bf16_f32 v41, v42, v43
	v_or_b32_e32 v42, 32, v62
	v_mov_b32_e32 v43, v69
	global_store_dwordx2 v[46:47], v[44:45], off
	v_lshl_add_u64 v[44:45], v[48:49], 0, v[42:43]
	v_cvt_pk_bf16_f32 v36, v36, v37
	v_cvt_pk_bf16_f32 v37, v38, v39
	v_or_b32_e32 v38, 64, v62
	v_mov_b32_e32 v39, v69
	global_store_dwordx2 v[44:45], v[40:41], off
	v_lshl_add_u64 v[40:41], v[48:49], 0, v[38:39]
	v_cvt_pk_bf16_f32 v32, v32, v33
	v_cvt_pk_bf16_f32 v33, v34, v35
	v_or_b32_e32 v34, 0x60, v62
	v_mov_b32_e32 v35, v69
	global_store_dwordx2 v[40:41], v[36:37], off
	v_lshl_add_u64 v[36:37], v[48:49], 0, v[34:35]
	s_mov_b64 s[0:1], 0x4000
	global_store_dwordx2 v[36:37], v[32:33], off
	v_lshl_add_u64 v[32:33], v[78:79], 0, s[0:1]
	v_cvt_pk_bf16_f32 v16, v16, v17
	v_cvt_pk_bf16_f32 v17, v18, v19
	v_lshl_add_u64 v[18:19], v[32:33], 0, v[34:35]
	s_mov_b64 s[0:1], 0x6000
	global_store_dwordx2 v[18:19], v[16:17], off
	v_lshl_add_u64 v[16:17], v[78:79], 0, s[0:1]
	v_readlane_b32 s0, v181, 50
	s_add_i32 s6, s6, s84
	s_add_i32 s12, s12, s0
	v_cvt_pk_bf16_f32 v56, v56, v57
	v_cvt_pk_bf16_f32 v57, v58, v59
	v_cvt_pk_bf16_f32 v52, v52, v53
	v_cvt_pk_bf16_f32 v53, v54, v55
	v_cvt_pk_bf16_f32 v28, v28, v29
	v_cvt_pk_bf16_f32 v29, v30, v31
	v_lshl_add_u64 v[30:31], v[32:33], 0, v[62:63]
	v_cvt_pk_bf16_f32 v24, v24, v25
	v_cvt_pk_bf16_f32 v25, v26, v27
	v_lshl_add_u64 v[26:27], v[32:33], 0, v[42:43]
	v_cvt_pk_bf16_f32 v20, v20, v21
	v_cvt_pk_bf16_f32 v21, v22, v23
	v_lshl_add_u64 v[22:23], v[32:33], 0, v[38:39]
	v_cvt_pk_bf16_f32 v12, v12, v13
	v_cvt_pk_bf16_f32 v13, v14, v15
	v_lshl_add_u64 v[14:15], v[16:17], 0, v[62:63]
	v_cvt_pk_bf16_f32 v8, v8, v9
	v_cvt_pk_bf16_f32 v9, v10, v11
	v_lshl_add_u64 v[10:11], v[16:17], 0, v[42:43]
	v_cvt_pk_bf16_f32 v4, v4, v5
	v_cvt_pk_bf16_f32 v5, v6, v7
	v_lshl_add_u64 v[6:7], v[16:17], 0, v[38:39]
	v_cvt_pk_bf16_f32 v0, v0, v1
	v_cvt_pk_bf16_f32 v1, v2, v3
	v_lshl_add_u64 v[2:3], v[16:17], 0, v[34:35]
	s_cmpk_lt_i32 s6, 0x800
	global_store_dwordx2 v[80:81], v[60:61], off
	global_store_dwordx2 v[80:81], v[56:57], off offset:32
	global_store_dwordx2 v[80:81], v[52:53], off offset:64
	global_store_dwordx2 v[30:31], v[28:29], off
	global_store_dwordx2 v[26:27], v[24:25], off
	global_store_dwordx2 v[22:23], v[20:21], off
	global_store_dwordx2 v[14:15], v[12:13], off
	global_store_dwordx2 v[10:11], v[8:9], off
	global_store_dwordx2 v[6:7], v[4:5], off
	global_store_dwordx2 v[2:3], v[0:1], off
	s_cbranch_scc1 .LBB0_1234
	v_readlane_b32 s50, v180, 0
	s_mov_b32 s18, 0x42ce8ed0
	s_mov_b32 s19, 0xc2b17218
	s_mov_b32 s48, s5
	v_readlane_b32 s51, v180, 1

.LBB0_1487:
	s_setprio 3
	s_and_b32 s6, s0, 0x2000
	s_xor_b32 s8, s6, 0x2000
	s_lshl_b32 s101, s8, 1
	s_add_u32 s101, s101, s100
	s_add_u32 m0, s101, 0x0
	s_nop 0
	global_load_lds_dwordx4 v[184:185], off
	s_add_u32 m0, s101, 0x1000
	v_lshl_add_u64 v[184:185], v[184:185], 0, vcc
	global_load_lds_dwordx4 v[186:187], off
	s_add_u32 m0, s101, 0x2000
	v_lshl_add_u64 v[186:187], v[186:187], 0, vcc
	global_load_lds_dwordx4 v[188:189], off
	s_add_u32 m0, s101, 0x3000
	v_lshl_add_u64 v[188:189], v[188:189], 0, vcc
	global_load_lds_dwordx4 v[190:191], off
	s_add_u32 m0, s101, 0x8000
	v_lshl_add_u64 v[190:191], v[190:191], 0, vcc
	global_load_lds_dwordx4 v[192:193], off
	s_add_u32 m0, s101, 0x9000
	v_lshl_add_u64 v[192:193], v[192:193], 0, vcc
	global_load_lds_dwordx4 v[194:195], off
	s_add_u32 m0, s101, 0xa000
	v_lshl_add_u64 v[194:195], v[194:195], 0, vcc
	global_load_lds_dwordx4 v[196:197], off
	s_add_u32 m0, s101, 0xb000
	v_lshl_add_u64 v[196:197], v[196:197], 0, vcc
	global_load_lds_dwordx4 v[198:199], off
	v_lshl_add_u64 v[198:199], v[198:199], 0, vcc
	s_lshl_b32 s6, s6, 1
	v_add_u32_e32 v148, s6, v92
	v_add_u32_e32 v149, s6, v71
	v_add_u32_e32 v128, v148, v98
	v_add_u32_e32 v144, v149, v98
	ds_read_b128 v[100:103], v128
	ds_read_b128 v[120:123], v128 offset:2048
	ds_read_b128 v[124:127], v128 offset:4096
	ds_read_b128 v[128:131], v128 offset:6144
	ds_read_b128 v[132:135], v144 offset:32768
	ds_read_b128 v[136:139], v144 offset:34816
	ds_read_b128 v[140:143], v144 offset:36864
	ds_read_b128 v[144:147], v144 offset:38912
	v_add_u32_e32 v232, v148, v99
	v_add_u32_e32 v233, v149, v99
	ds_read_b128 v[200:203], v232
	ds_read_b128 v[204:207], v232 offset:2048
	ds_read_b128 v[208:211], v232 offset:4096
	ds_read_b128 v[212:215], v232 offset:6144
	ds_read_b128 v[216:219], v233 offset:32768
	ds_read_b128 v[220:223], v233 offset:34816
	ds_read_b128 v[224:227], v233 offset:36864
	ds_read_b128 v[228:231], v233 offset:38912
	s_setprio 1
	s_waitcnt lgkmcnt(8)
	v_mfma_f32_16x16x32_bf16 v[60:63], v[132:135], v[100:103], v[60:63]
	v_mfma_f32_16x16x32_bf16 v[56:59], v[136:139], v[100:103], v[56:59]
	v_mfma_f32_16x16x32_bf16 v[52:55], v[140:143], v[100:103], v[52:55]
	v_mfma_f32_16x16x32_bf16 v[48:51], v[144:147], v[100:103], v[48:51]
	v_mfma_f32_16x16x32_bf16 v[44:47], v[132:135], v[120:123], v[44:47]
	v_mfma_f32_16x16x32_bf16 v[40:43], v[136:139], v[120:123], v[40:43]
	v_mfma_f32_16x16x32_bf16 v[36:39], v[140:143], v[120:123], v[36:39]
	v_mfma_f32_16x16x32_bf16 v[32:35], v[144:147], v[120:123], v[32:35]
	v_mfma_f32_16x16x32_bf16 v[28:31], v[132:135], v[124:127], v[28:31]
	v_mfma_f32_16x16x32_bf16 v[24:27], v[136:139], v[124:127], v[24:27]
	v_mfma_f32_16x16x32_bf16 v[20:23], v[140:143], v[124:127], v[20:23]
	v_mfma_f32_16x16x32_bf16 v[16:19], v[144:147], v[124:127], v[16:19]
	v_mfma_f32_16x16x32_bf16 v[12:15], v[132:135], v[128:131], v[12:15]
	v_mfma_f32_16x16x32_bf16 v[8:11], v[136:139], v[128:131], v[8:11]
	v_mfma_f32_16x16x32_bf16 v[4:7], v[140:143], v[128:131], v[4:7]
	v_mfma_f32_16x16x32_bf16 v[0:3], v[144:147], v[128:131], v[0:3]
	s_waitcnt lgkmcnt(0)
	v_mfma_f32_16x16x32_bf16 v[60:63], v[216:219], v[200:203], v[60:63]
	v_mfma_f32_16x16x32_bf16 v[56:59], v[220:223], v[200:203], v[56:59]
	v_mfma_f32_16x16x32_bf16 v[52:55], v[224:227], v[200:203], v[52:55]
	v_mfma_f32_16x16x32_bf16 v[48:51], v[228:231], v[200:203], v[48:51]
	v_mfma_f32_16x16x32_bf16 v[44:47], v[216:219], v[204:207], v[44:47]
	v_mfma_f32_16x16x32_bf16 v[40:43], v[220:223], v[204:207], v[40:43]
	v_mfma_f32_16x16x32_bf16 v[36:39], v[224:227], v[204:207], v[36:39]
	v_mfma_f32_16x16x32_bf16 v[32:35], v[228:231], v[204:207], v[32:35]
	v_mfma_f32_16x16x32_bf16 v[28:31], v[216:219], v[208:211], v[28:31]
	v_mfma_f32_16x16x32_bf16 v[24:27], v[220:223], v[208:211], v[24:27]
	v_mfma_f32_16x16x32_bf16 v[20:23], v[224:227], v[208:211], v[20:23]
	v_mfma_f32_16x16x32_bf16 v[16:19], v[228:231], v[208:211], v[16:19]
	v_mfma_f32_16x16x32_bf16 v[12:15], v[216:219], v[212:215], v[12:15]
	v_mfma_f32_16x16x32_bf16 v[8:11], v[220:223], v[212:215], v[8:11]
	v_mfma_f32_16x16x32_bf16 v[4:7], v[224:227], v[212:215], v[4:7]
	v_mfma_f32_16x16x32_bf16 v[0:3], v[228:231], v[212:215], v[0:3]
	s_setprio 0
	s_waitcnt vmcnt(0)
	s_add_u32 s36, s36, 0x80
	s_addc_u32 s37, s37, 0
	s_addk_i32 s0, 0x2000
	s_cmpk_lg_i32 s36, 0xf80
	s_waitcnt vmcnt(0)
	s_barrier
	s_cbranch_scc1 .LBB0_1487
	ds_read_b128 v[88:91], v94 offset:16384
	ds_read_b128 v[100:103], v94 offset:18432
	ds_read_b128 v[120:123], v94 offset:20480
	ds_read_b128 v[124:127], v94 offset:22528
	ds_read_b128 v[128:131], v95 offset:49152
	ds_read_b128 v[132:135], v95 offset:51200
	ds_read_b128 v[136:139], v95 offset:53248
	ds_read_b128 v[140:143], v95 offset:55296
	s_setprio 1
	s_waitcnt lgkmcnt(3)
	v_mfma_f32_16x16x32_bf16 v[60:63], v[128:131], v[88:91], v[60:63]
	s_waitcnt lgkmcnt(2)
	v_mfma_f32_16x16x32_bf16 v[56:59], v[132:135], v[88:91], v[56:59]
	s_waitcnt lgkmcnt(1)
	v_mfma_f32_16x16x32_bf16 v[52:55], v[136:139], v[88:91], v[52:55]
	s_waitcnt lgkmcnt(0)
	v_mfma_f32_16x16x32_bf16 v[48:51], v[140:143], v[88:91], v[48:51]
	v_mfma_f32_16x16x32_bf16 v[40:43], v[132:135], v[100:103], v[40:43]
	v_mfma_f32_16x16x32_bf16 v[36:39], v[136:139], v[100:103], v[36:39]
	v_mfma_f32_16x16x32_bf16 v[32:35], v[140:143], v[100:103], v[32:35]
	v_mfma_f32_16x16x32_bf16 v[20:23], v[136:139], v[120:123], v[20:23]
	v_mfma_f32_16x16x32_bf16 v[16:19], v[140:143], v[120:123], v[16:19]
	v_mfma_f32_16x16x32_bf16 v[0:3], v[140:143], v[124:127], v[0:3]
	v_mfma_f32_16x16x32_bf16 v[88:91], v[128:131], v[100:103], v[44:47]
	v_mfma_f32_16x16x32_bf16 v[100:103], v[128:131], v[120:123], v[28:31]
	v_mfma_f32_16x16x32_bf16 v[144:147], v[132:135], v[120:123], v[24:27]
	v_mfma_f32_16x16x32_bf16 v[120:123], v[128:131], v[124:127], v[12:15]
	v_mfma_f32_16x16x32_bf16 v[128:131], v[132:135], v[124:127], v[8:11]
	v_mfma_f32_16x16x32_bf16 v[132:135], v[136:139], v[124:127], v[4:7]
	s_setprio 0
	s_nop 1
	ds_read_b128 v[4:7], v96 offset:16384
	ds_read_b128 v[8:11], v96 offset:18432
	ds_read_b128 v[124:127], v96 offset:20480
	ds_read_b128 v[136:139], v96 offset:22528
	ds_read_b128 v[140:143], v97 offset:49152
	ds_read_b128 v[148:151], v97 offset:51200
	ds_read_b128 v[152:155], v97 offset:53248
	ds_read_b128 v[156:159], v97 offset:55296
	s_setprio 1
	s_waitcnt lgkmcnt(3)
	v_mfma_f32_16x16x32_bf16 v[60:63], v[140:143], v[4:7], v[60:63]
	s_waitcnt lgkmcnt(2)
	v_mfma_f32_16x16x32_bf16 v[44:47], v[148:151], v[4:7], v[56:59]
	s_waitcnt lgkmcnt(1)
	v_mfma_f32_16x16x32_bf16 v[28:31], v[152:155], v[4:7], v[52:55]
	s_waitcnt lgkmcnt(0)
	v_mfma_f32_16x16x32_bf16 v[12:15], v[156:159], v[4:7], v[48:51]
	v_mfma_f32_16x16x32_bf16 v[56:59], v[140:143], v[8:11], v[88:91]
	v_mfma_f32_16x16x32_bf16 v[40:43], v[148:151], v[8:11], v[40:43]
	v_mfma_f32_16x16x32_bf16 v[24:27], v[152:155], v[8:11], v[36:39]
	v_mfma_f32_16x16x32_bf16 v[8:11], v[156:159], v[8:11], v[32:35]
	v_mfma_f32_16x16x32_bf16 v[52:55], v[140:143], v[124:127], v[100:103]
	v_mfma_f32_16x16x32_bf16 v[36:39], v[148:151], v[124:127], v[144:147]
	v_mfma_f32_16x16x32_bf16 v[20:23], v[152:155], v[124:127], v[20:23]
	v_mfma_f32_16x16x32_bf16 v[4:7], v[156:159], v[124:127], v[16:19]
	v_mfma_f32_16x16x32_bf16 v[48:51], v[140:143], v[136:139], v[120:123]
	v_mfma_f32_16x16x32_bf16 v[32:35], v[148:151], v[136:139], v[128:131]
	v_mfma_f32_16x16x32_bf16 v[16:19], v[152:155], v[136:139], v[132:135]
	v_mfma_f32_16x16x32_bf16 v[0:3], v[156:159], v[136:139], v[0:3]
	s_setprio 0
	s_waitcnt vmcnt(0)
	s_cmpk_gt_i32 s1, 0x7f
	s_barrier
	s_cbranch_scc0 .LBB0_1490
	s_add_i32 s0, s24, 0xffffc000
	s_lshr_b32 s0, s0, 8
	v_readlane_b32 s6, v180, 24
	s_add_i32 s6, s0, s6
	s_and_b32 s10, s24, 0x80
	s_lshl_b64 s[8:9], s[6:7], 8
	v_readlane_b32 s36, v182, 19
	s_or_b32 s8, s8, s10
	s_mov_b64 s[10:11], 0
	v_readlane_b32 s37, v182, 20
	s_branch .LBB0_1491

.LBB0_1498:
	s_setprio 3
	s_and_b32 s10, s6, 0x2000
	s_xor_b32 s8, s10, 0x2000
	s_lshl_b32 s101, s8, 1
	s_add_u32 s101, s101, s100
	s_add_u32 m0, s101, 0x0
	s_nop 0
	global_load_lds_dwordx4 v[184:185], off
	s_add_u32 m0, s101, 0x1000
	v_lshl_add_u64 v[184:185], v[184:185], 0, vcc
	global_load_lds_dwordx4 v[186:187], off
	s_add_u32 m0, s101, 0x2000
	v_lshl_add_u64 v[186:187], v[186:187], 0, vcc
	global_load_lds_dwordx4 v[188:189], off
	s_add_u32 m0, s101, 0x3000
	v_lshl_add_u64 v[188:189], v[188:189], 0, vcc
	global_load_lds_dwordx4 v[190:191], off
	s_add_u32 m0, s101, 0x8000
	v_lshl_add_u64 v[190:191], v[190:191], 0, vcc
	global_load_lds_dwordx4 v[192:193], off
	s_add_u32 m0, s101, 0x9000
	v_lshl_add_u64 v[192:193], v[192:193], 0, vcc
	global_load_lds_dwordx4 v[194:195], off
	s_add_u32 m0, s101, 0xa000
	v_lshl_add_u64 v[194:195], v[194:195], 0, vcc
	global_load_lds_dwordx4 v[196:197], off
	s_add_u32 m0, s101, 0xb000
	v_lshl_add_u64 v[196:197], v[196:197], 0, vcc
	global_load_lds_dwordx4 v[198:199], off
	v_lshl_add_u64 v[198:199], v[198:199], 0, vcc
	s_lshl_b32 s8, s10, 1
	v_add_u32_e32 v68, s8, v84
	v_add_u32_e32 v140, s8, v83
	v_add_u32_e32 v120, v68, v90
	v_add_u32_e32 v136, v140, v90
	ds_read_b128 v[92:95], v120
	ds_read_b128 v[96:99], v120 offset:2048
	ds_read_b128 v[100:103], v120 offset:4096
	ds_read_b128 v[120:123], v120 offset:6144
	ds_read_b128 v[124:127], v136 offset:32768
	ds_read_b128 v[128:131], v136 offset:34816
	ds_read_b128 v[132:135], v136 offset:36864
	ds_read_b128 v[136:139], v136 offset:38912
	v_add_u32_e32 v68, v68, v91
	ds_read_b128 v[200:203], v68
	ds_read_b128 v[204:207], v68 offset:2048
	ds_read_b128 v[208:211], v68 offset:4096
	ds_read_b128 v[212:215], v68 offset:6144
	v_add_u32_e32 v68, v140, v91
	ds_read_b128 v[216:219], v68 offset:32768
	ds_read_b128 v[220:223], v68 offset:34816
	ds_read_b128 v[224:227], v68 offset:36864
	ds_read_b128 v[228:231], v68 offset:38912
	s_setprio 1
	s_waitcnt lgkmcnt(8)
	v_mfma_f32_16x16x32_bf16 v[60:63], v[124:127], v[92:95], v[60:63]
	v_mfma_f32_16x16x32_bf16 v[56:59], v[128:131], v[92:95], v[56:59]
	v_mfma_f32_16x16x32_bf16 v[52:55], v[132:135], v[92:95], v[52:55]
	v_mfma_f32_16x16x32_bf16 v[48:51], v[136:139], v[92:95], v[48:51]
	v_mfma_f32_16x16x32_bf16 v[44:47], v[124:127], v[96:99], v[44:47]
	v_mfma_f32_16x16x32_bf16 v[40:43], v[128:131], v[96:99], v[40:43]
	v_mfma_f32_16x16x32_bf16 v[36:39], v[132:135], v[96:99], v[36:39]
	v_mfma_f32_16x16x32_bf16 v[32:35], v[136:139], v[96:99], v[32:35]
	v_mfma_f32_16x16x32_bf16 v[28:31], v[124:127], v[100:103], v[28:31]
	v_mfma_f32_16x16x32_bf16 v[24:27], v[128:131], v[100:103], v[24:27]
	v_mfma_f32_16x16x32_bf16 v[20:23], v[132:135], v[100:103], v[20:23]
	v_mfma_f32_16x16x32_bf16 v[16:19], v[136:139], v[100:103], v[16:19]
	v_mfma_f32_16x16x32_bf16 v[12:15], v[124:127], v[120:123], v[12:15]
	v_mfma_f32_16x16x32_bf16 v[8:11], v[128:131], v[120:123], v[8:11]
	v_mfma_f32_16x16x32_bf16 v[4:7], v[132:135], v[120:123], v[4:7]
	v_mfma_f32_16x16x32_bf16 v[0:3], v[136:139], v[120:123], v[0:3]
	s_waitcnt lgkmcnt(0)
	v_mfma_f32_16x16x32_bf16 v[60:63], v[216:219], v[200:203], v[60:63]
	v_mfma_f32_16x16x32_bf16 v[56:59], v[220:223], v[200:203], v[56:59]
	v_mfma_f32_16x16x32_bf16 v[52:55], v[224:227], v[200:203], v[52:55]
	v_mfma_f32_16x16x32_bf16 v[48:51], v[228:231], v[200:203], v[48:51]
	v_mfma_f32_16x16x32_bf16 v[44:47], v[216:219], v[204:207], v[44:47]
	v_mfma_f32_16x16x32_bf16 v[40:43], v[220:223], v[204:207], v[40:43]
	v_mfma_f32_16x16x32_bf16 v[36:39], v[224:227], v[204:207], v[36:39]
	v_mfma_f32_16x16x32_bf16 v[32:35], v[228:231], v[204:207], v[32:35]
	v_mfma_f32_16x16x32_bf16 v[28:31], v[216:219], v[208:211], v[28:31]
	v_mfma_f32_16x16x32_bf16 v[24:27], v[220:223], v[208:211], v[24:27]
	v_mfma_f32_16x16x32_bf16 v[20:23], v[224:227], v[208:211], v[20:23]
	v_mfma_f32_16x16x32_bf16 v[16:19], v[228:231], v[208:211], v[16:19]
	v_mfma_f32_16x16x32_bf16 v[12:15], v[216:219], v[212:215], v[12:15]
	v_mfma_f32_16x16x32_bf16 v[8:11], v[220:223], v[212:215], v[8:11]
	v_mfma_f32_16x16x32_bf16 v[4:7], v[224:227], v[212:215], v[4:7]
	v_mfma_f32_16x16x32_bf16 v[0:3], v[228:231], v[212:215], v[0:3]
	s_setprio 0
	s_addk_i32 s6, 0x2000
	s_waitcnt vmcnt(0)
	s_add_u32 s36, s36, 0x80
	s_addc_u32 s37, s37, 0
	s_cmpk_lg_i32 s36, 0x780
	s_waitcnt vmcnt(0)
	s_barrier
	s_cbranch_scc1 .LBB0_1498
	ds_read_b128 v[78:81], v85 offset:55296
	ds_read_b128 v[92:95], v85 offset:53248
	ds_read_b128 v[96:99], v85 offset:51200
	ds_read_b128 v[100:103], v85 offset:49152
	ds_read_b128 v[120:123], v86 offset:22528
	ds_read_b128 v[124:127], v86 offset:20480
	ds_read_b128 v[128:131], v86 offset:18432
	ds_read_b128 v[132:135], v86 offset:16384
	s_setprio 1
	s_waitcnt lgkmcnt(0)
	v_mfma_f32_16x16x32_bf16 v[60:63], v[100:103], v[132:135], v[60:63]
	v_mfma_f32_16x16x32_bf16 v[56:59], v[96:99], v[132:135], v[56:59]
	v_mfma_f32_16x16x32_bf16 v[52:55], v[92:95], v[132:135], v[52:55]
	v_mfma_f32_16x16x32_bf16 v[48:51], v[78:81], v[132:135], v[48:51]
	v_mfma_f32_16x16x32_bf16 v[44:47], v[100:103], v[128:131], v[44:47]
	v_mfma_f32_16x16x32_bf16 v[40:43], v[96:99], v[128:131], v[40:43]
	v_mfma_f32_16x16x32_bf16 v[36:39], v[92:95], v[128:131], v[36:39]
	v_mfma_f32_16x16x32_bf16 v[32:35], v[78:81], v[128:131], v[32:35]
	v_mfma_f32_16x16x32_bf16 v[28:31], v[100:103], v[124:127], v[28:31]
	v_mfma_f32_16x16x32_bf16 v[24:27], v[96:99], v[124:127], v[24:27]
	v_mfma_f32_16x16x32_bf16 v[20:23], v[92:95], v[124:127], v[20:23]
	v_mfma_f32_16x16x32_bf16 v[16:19], v[78:81], v[124:127], v[16:19]
	v_mfma_f32_16x16x32_bf16 v[12:15], v[100:103], v[120:123], v[12:15]
	v_mfma_f32_16x16x32_bf16 v[8:11], v[96:99], v[120:123], v[8:11]
	v_mfma_f32_16x16x32_bf16 v[4:7], v[92:95], v[120:123], v[4:7]
	v_mfma_f32_16x16x32_bf16 v[0:3], v[78:81], v[120:123], v[0:3]
	s_setprio 0
	ds_read_b128 v[78:81], v87 offset:16384
	ds_read_b128 v[92:95], v87 offset:18432
	ds_read_b128 v[96:99], v87 offset:20480
	ds_read_b128 v[100:103], v87 offset:22528
	ds_read_b128 v[120:123], v88 offset:49152
	ds_read_b128 v[124:127], v88 offset:51200
	ds_read_b128 v[128:131], v88 offset:53248
	ds_read_b128 v[132:135], v88 offset:55296
	s_setprio 1
	s_waitcnt lgkmcnt(3)
	v_mfma_f32_16x16x32_bf16 v[60:63], v[120:123], v[78:81], v[60:63]
	s_waitcnt lgkmcnt(2)
	v_mfma_f32_16x16x32_bf16 v[56:59], v[124:127], v[78:81], v[56:59]
	s_waitcnt lgkmcnt(1)
	v_mfma_f32_16x16x32_bf16 v[52:55], v[128:131], v[78:81], v[52:55]
	s_waitcnt lgkmcnt(0)
	v_mfma_f32_16x16x32_bf16 v[48:51], v[132:135], v[78:81], v[48:51]
	v_mfma_f32_16x16x32_bf16 v[44:47], v[120:123], v[92:95], v[44:47]
	v_mfma_f32_16x16x32_bf16 v[40:43], v[124:127], v[92:95], v[40:43]
	v_mfma_f32_16x16x32_bf16 v[36:39], v[128:131], v[92:95], v[36:39]
	v_mfma_f32_16x16x32_bf16 v[32:35], v[132:135], v[92:95], v[32:35]
	v_mfma_f32_16x16x32_bf16 v[28:31], v[120:123], v[96:99], v[28:31]
	v_mfma_f32_16x16x32_bf16 v[24:27], v[124:127], v[96:99], v[24:27]
	v_mfma_f32_16x16x32_bf16 v[20:23], v[128:131], v[96:99], v[20:23]
	v_mfma_f32_16x16x32_bf16 v[16:19], v[132:135], v[96:99], v[16:19]
	v_mfma_f32_16x16x32_bf16 v[12:15], v[120:123], v[100:103], v[12:15]
	v_mfma_f32_16x16x32_bf16 v[8:11], v[124:127], v[100:103], v[8:11]
	v_mfma_f32_16x16x32_bf16 v[4:7], v[128:131], v[100:103], v[4:7]
	v_mfma_f32_16x16x32_bf16 v[0:3], v[132:135], v[100:103], v[0:3]
	s_setprio 0
	s_ashr_i32 s1, s1, 4
	s_mul_hi_i32 s6, s1, 0x4200000
	s_mul_i32 s1, s1, 0x4200000
	s_add_u32 s8, s90, s1
	v_add_u32_e32 v78, s20, v71
	s_addc_u32 s9, s91, s6
	s_and_b32 s1, s24, 0x780
	v_ashrrev_i32_e32 v79, 31, v78
	v_or_b32_e32 v68, s1, v89
	v_lshlrev_b64 v[80:81], 12, v[78:79]
	v_lshl_add_u64 v[80:81], s[8:9], 0, v[80:81]
	v_lshlrev_b32_e32 v68, 1, v68
	v_cvt_pk_bf16_f32 v60, v60, v61
	v_cvt_pk_bf16_f32 v61, v62, v63
	v_lshl_add_u64 v[62:63], v[80:81], 0, v[68:69]
	v_cvt_pk_bf16_f32 v48, v48, v49
	v_cvt_pk_bf16_f32 v49, v50, v51
	s_waitcnt vmcnt(0)
	s_barrier
	global_store_dwordx2 v[62:63], v[48:49], off offset:96
	v_or_b32_e32 v48, 16, v78
	v_ashrrev_i32_e32 v49, 31, v48
	v_lshlrev_b64 v[48:49], 12, v[48:49]
	v_lshl_add_u64 v[48:49], s[8:9], 0, v[48:49]
	v_cvt_pk_bf16_f32 v44, v44, v45
	v_cvt_pk_bf16_f32 v45, v46, v47
	v_lshl_add_u64 v[46:47], v[48:49], 0, v[68:69]
	v_cvt_pk_bf16_f32 v32, v32, v33
	v_cvt_pk_bf16_f32 v33, v34, v35
	global_store_dwordx2 v[46:47], v[32:33], off offset:96
	v_or_b32_e32 v32, 32, v78
	v_ashrrev_i32_e32 v33, 31, v32
	v_lshlrev_b64 v[32:33], 12, v[32:33]
	v_lshl_add_u64 v[32:33], s[8:9], 0, v[32:33]
	v_cvt_pk_bf16_f32 v28, v28, v29
	v_cvt_pk_bf16_f32 v29, v30, v31
	v_lshl_add_u64 v[30:31], v[32:33], 0, v[68:69]
	v_cvt_pk_bf16_f32 v16, v16, v17
	v_cvt_pk_bf16_f32 v17, v18, v19
	global_store_dwordx2 v[30:31], v[16:17], off offset:96
	v_or_b32_e32 v16, 48, v78
	v_ashrrev_i32_e32 v17, 31, v16
	v_lshlrev_b64 v[16:17], 12, v[16:17]
	v_lshl_add_u64 v[16:17], s[8:9], 0, v[16:17]
	s_add_i32 s0, s0, s84
	v_cvt_pk_bf16_f32 v56, v56, v57
	v_cvt_pk_bf16_f32 v57, v58, v59
	v_cvt_pk_bf16_f32 v52, v52, v53
	v_cvt_pk_bf16_f32 v53, v54, v55
	v_cvt_pk_bf16_f32 v40, v40, v41
	v_cvt_pk_bf16_f32 v41, v42, v43
	v_cvt_pk_bf16_f32 v36, v36, v37
	v_cvt_pk_bf16_f32 v37, v38, v39
	v_cvt_pk_bf16_f32 v24, v24, v25
	v_cvt_pk_bf16_f32 v25, v26, v27
	v_cvt_pk_bf16_f32 v20, v20, v21
	v_cvt_pk_bf16_f32 v21, v22, v23
	v_cvt_pk_bf16_f32 v12, v12, v13
	v_cvt_pk_bf16_f32 v13, v14, v15
	v_lshl_add_u64 v[14:15], v[16:17], 0, v[68:69]
	v_cvt_pk_bf16_f32 v8, v8, v9
	v_cvt_pk_bf16_f32 v9, v10, v11
	v_cvt_pk_bf16_f32 v4, v4, v5
	v_cvt_pk_bf16_f32 v5, v6, v7
	v_cvt_pk_bf16_f32 v0, v0, v1
	v_cvt_pk_bf16_f32 v1, v2, v3
	s_cmpk_lt_i32 s0, 0x18c0
	global_store_dwordx2 v[62:63], v[60:61], off
	global_store_dwordx2 v[62:63], v[56:57], off offset:32
	global_store_dwordx2 v[62:63], v[52:53], off offset:64
	global_store_dwordx2 v[46:47], v[44:45], off
	global_store_dwordx2 v[46:47], v[40:41], off offset:32
	global_store_dwordx2 v[46:47], v[36:37], off offset:64
	global_store_dwordx2 v[30:31], v[28:29], off
	global_store_dwordx2 v[30:31], v[24:25], off offset:32
	global_store_dwordx2 v[30:31], v[20:21], off offset:64
	global_store_dwordx2 v[14:15], v[12:13], off
	global_store_dwordx2 v[14:15], v[8:9], off offset:32
	global_store_dwordx2 v[14:15], v[4:5], off offset:64
	global_store_dwordx2 v[14:15], v[0:1], off offset:96
	s_cbranch_scc1 .LBB0_1497

.LBB0_1707:
	s_setprio 3
	s_and_b32 s6, s0, 0x2000
	s_xor_b32 s8, s6, 0x2000
	s_lshl_b32 s101, s8, 1
	s_add_u32 s101, s101, s100
	s_add_u32 m0, s101, 0x0
	s_nop 0
	global_load_lds_dwordx4 v[184:185], off
	s_add_u32 m0, s101, 0x1000
	v_lshl_add_u64 v[184:185], v[184:185], 0, vcc
	global_load_lds_dwordx4 v[186:187], off
	s_add_u32 m0, s101, 0x2000
	v_lshl_add_u64 v[186:187], v[186:187], 0, vcc
	global_load_lds_dwordx4 v[188:189], off
	s_add_u32 m0, s101, 0x3000
	v_lshl_add_u64 v[188:189], v[188:189], 0, vcc
	global_load_lds_dwordx4 v[190:191], off
	s_add_u32 m0, s101, 0x8000
	v_lshl_add_u64 v[190:191], v[190:191], 0, vcc
	global_load_lds_dwordx4 v[192:193], off
	s_add_u32 m0, s101, 0x9000
	v_lshl_add_u64 v[192:193], v[192:193], 0, vcc
	global_load_lds_dwordx4 v[194:195], off
	s_add_u32 m0, s101, 0xa000
	v_lshl_add_u64 v[194:195], v[194:195], 0, vcc
	global_load_lds_dwordx4 v[196:197], off
	s_add_u32 m0, s101, 0xb000
	v_lshl_add_u64 v[196:197], v[196:197], 0, vcc
	global_load_lds_dwordx4 v[198:199], off
	v_lshl_add_u64 v[198:199], v[198:199], 0, vcc
	s_lshl_b32 s6, s6, 1
	v_add_u32_e32 v102, s6, v90
	v_add_u32_e32 v103, s6, v71
	v_add_u32_e32 v128, v102, v96
	v_add_u32_e32 v144, v103, v96
	ds_read_b128 v[98:101], v128
	ds_read_b128 v[120:123], v128 offset:2048
	ds_read_b128 v[124:127], v128 offset:4096
	ds_read_b128 v[128:131], v128 offset:6144
	ds_read_b128 v[132:135], v144 offset:32768
	ds_read_b128 v[136:139], v144 offset:34816
	ds_read_b128 v[140:143], v144 offset:36864
	ds_read_b128 v[144:147], v144 offset:38912
	v_add_u32_e32 v102, v102, v97
	ds_read_b128 v[200:203], v102
	ds_read_b128 v[204:207], v102 offset:2048
	ds_read_b128 v[208:211], v102 offset:4096
	ds_read_b128 v[212:215], v102 offset:6144
	v_add_u32_e32 v102, v103, v97
	ds_read_b128 v[216:219], v102 offset:32768
	ds_read_b128 v[220:223], v102 offset:34816
	ds_read_b128 v[224:227], v102 offset:36864
	ds_read_b128 v[228:231], v102 offset:38912
	s_setprio 1
	s_waitcnt lgkmcnt(8)
	v_mfma_f32_16x16x32_bf16 v[60:63], v[132:135], v[98:101], v[60:63]
	v_mfma_f32_16x16x32_bf16 v[56:59], v[136:139], v[98:101], v[56:59]
	v_mfma_f32_16x16x32_bf16 v[52:55], v[140:143], v[98:101], v[52:55]
	v_mfma_f32_16x16x32_bf16 v[48:51], v[144:147], v[98:101], v[48:51]
	v_mfma_f32_16x16x32_bf16 v[44:47], v[132:135], v[120:123], v[44:47]
	v_mfma_f32_16x16x32_bf16 v[40:43], v[136:139], v[120:123], v[40:43]
	v_mfma_f32_16x16x32_bf16 v[36:39], v[140:143], v[120:123], v[36:39]
	v_mfma_f32_16x16x32_bf16 v[32:35], v[144:147], v[120:123], v[32:35]
	v_mfma_f32_16x16x32_bf16 v[28:31], v[132:135], v[124:127], v[28:31]
	v_mfma_f32_16x16x32_bf16 v[24:27], v[136:139], v[124:127], v[24:27]
	v_mfma_f32_16x16x32_bf16 v[20:23], v[140:143], v[124:127], v[20:23]
	v_mfma_f32_16x16x32_bf16 v[16:19], v[144:147], v[124:127], v[16:19]
	v_mfma_f32_16x16x32_bf16 v[12:15], v[132:135], v[128:131], v[12:15]
	v_mfma_f32_16x16x32_bf16 v[8:11], v[136:139], v[128:131], v[8:11]
	v_mfma_f32_16x16x32_bf16 v[4:7], v[140:143], v[128:131], v[4:7]
	v_mfma_f32_16x16x32_bf16 v[0:3], v[144:147], v[128:131], v[0:3]
	s_waitcnt lgkmcnt(0)
	v_mfma_f32_16x16x32_bf16 v[60:63], v[216:219], v[200:203], v[60:63]
	v_mfma_f32_16x16x32_bf16 v[56:59], v[220:223], v[200:203], v[56:59]
	v_mfma_f32_16x16x32_bf16 v[52:55], v[224:227], v[200:203], v[52:55]
	v_mfma_f32_16x16x32_bf16 v[48:51], v[228:231], v[200:203], v[48:51]
	v_mfma_f32_16x16x32_bf16 v[44:47], v[216:219], v[204:207], v[44:47]
	v_mfma_f32_16x16x32_bf16 v[40:43], v[220:223], v[204:207], v[40:43]
	v_mfma_f32_16x16x32_bf16 v[36:39], v[224:227], v[204:207], v[36:39]
	v_mfma_f32_16x16x32_bf16 v[32:35], v[228:231], v[204:207], v[32:35]
	v_mfma_f32_16x16x32_bf16 v[28:31], v[216:219], v[208:211], v[28:31]
	v_mfma_f32_16x16x32_bf16 v[24:27], v[220:223], v[208:211], v[24:27]
	v_mfma_f32_16x16x32_bf16 v[20:23], v[224:227], v[208:211], v[20:23]
	v_mfma_f32_16x16x32_bf16 v[16:19], v[228:231], v[208:211], v[16:19]
	v_mfma_f32_16x16x32_bf16 v[12:15], v[216:219], v[212:215], v[12:15]
	v_mfma_f32_16x16x32_bf16 v[8:11], v[220:223], v[212:215], v[8:11]
	v_mfma_f32_16x16x32_bf16 v[4:7], v[224:227], v[212:215], v[4:7]
	v_mfma_f32_16x16x32_bf16 v[0:3], v[228:231], v[212:215], v[0:3]
	s_setprio 0
	s_waitcnt vmcnt(0)
	s_add_u32 s36, s36, 0x80
	s_addc_u32 s37, s37, 0
	s_addk_i32 s0, 0x2000
	s_cmpk_lg_i32 s36, 0xf80
	s_waitcnt vmcnt(0)
	s_barrier
	s_cbranch_scc1 .LBB0_1707
	ds_read_b128 v[86:89], v92 offset:16384
	ds_read_b128 v[98:101], v92 offset:18432
	ds_read_b128 v[120:123], v92 offset:20480
	ds_read_b128 v[124:127], v92 offset:22528
	ds_read_b128 v[128:131], v93 offset:49152
	ds_read_b128 v[132:135], v93 offset:51200
	ds_read_b128 v[136:139], v93 offset:53248
	ds_read_b128 v[140:143], v93 offset:55296
	s_setprio 1
	s_waitcnt lgkmcnt(3)
	v_mfma_f32_16x16x32_bf16 v[60:63], v[128:131], v[86:89], v[60:63]
	s_waitcnt lgkmcnt(2)
	v_mfma_f32_16x16x32_bf16 v[56:59], v[132:135], v[86:89], v[56:59]
	s_waitcnt lgkmcnt(1)
	v_mfma_f32_16x16x32_bf16 v[52:55], v[136:139], v[86:89], v[52:55]
	s_waitcnt lgkmcnt(0)
	v_mfma_f32_16x16x32_bf16 v[48:51], v[140:143], v[86:89], v[48:51]
	v_mfma_f32_16x16x32_bf16 v[40:43], v[132:135], v[98:101], v[40:43]
	v_mfma_f32_16x16x32_bf16 v[36:39], v[136:139], v[98:101], v[36:39]
	v_mfma_f32_16x16x32_bf16 v[32:35], v[140:143], v[98:101], v[32:35]
	v_mfma_f32_16x16x32_bf16 v[20:23], v[136:139], v[120:123], v[20:23]
	v_mfma_f32_16x16x32_bf16 v[16:19], v[140:143], v[120:123], v[16:19]
	v_mfma_f32_16x16x32_bf16 v[0:3], v[140:143], v[124:127], v[0:3]
	v_mfma_f32_16x16x32_bf16 v[86:89], v[128:131], v[98:101], v[44:47]
	v_mfma_f32_16x16x32_bf16 v[98:101], v[128:131], v[120:123], v[28:31]
	v_mfma_f32_16x16x32_bf16 v[144:147], v[132:135], v[120:123], v[24:27]
	v_mfma_f32_16x16x32_bf16 v[120:123], v[128:131], v[124:127], v[12:15]
	v_mfma_f32_16x16x32_bf16 v[128:131], v[132:135], v[124:127], v[8:11]
	v_mfma_f32_16x16x32_bf16 v[132:135], v[136:139], v[124:127], v[4:7]
	s_setprio 0
	s_nop 1
	ds_read_b128 v[4:7], v94 offset:16384
	ds_read_b128 v[8:11], v94 offset:18432
	ds_read_b128 v[124:127], v94 offset:20480
	ds_read_b128 v[136:139], v94 offset:22528
	ds_read_b128 v[140:143], v95 offset:49152
	ds_read_b128 v[148:151], v95 offset:51200
	ds_read_b128 v[152:155], v95 offset:53248
	ds_read_b128 v[156:159], v95 offset:55296
	s_setprio 1
	s_waitcnt lgkmcnt(3)
	v_mfma_f32_16x16x32_bf16 v[60:63], v[140:143], v[4:7], v[60:63]
	s_waitcnt lgkmcnt(2)
	v_mfma_f32_16x16x32_bf16 v[44:47], v[148:151], v[4:7], v[56:59]
	s_waitcnt lgkmcnt(1)
	v_mfma_f32_16x16x32_bf16 v[28:31], v[152:155], v[4:7], v[52:55]
	s_waitcnt lgkmcnt(0)
	v_mfma_f32_16x16x32_bf16 v[12:15], v[156:159], v[4:7], v[48:51]
	v_mfma_f32_16x16x32_bf16 v[56:59], v[140:143], v[8:11], v[86:89]
	v_mfma_f32_16x16x32_bf16 v[40:43], v[148:151], v[8:11], v[40:43]
	v_mfma_f32_16x16x32_bf16 v[24:27], v[152:155], v[8:11], v[36:39]
	v_mfma_f32_16x16x32_bf16 v[8:11], v[156:159], v[8:11], v[32:35]
	v_mfma_f32_16x16x32_bf16 v[52:55], v[140:143], v[124:127], v[98:101]
	v_mfma_f32_16x16x32_bf16 v[36:39], v[148:151], v[124:127], v[144:147]
	v_mfma_f32_16x16x32_bf16 v[20:23], v[152:155], v[124:127], v[20:23]
	v_mfma_f32_16x16x32_bf16 v[4:7], v[156:159], v[124:127], v[16:19]
	v_mfma_f32_16x16x32_bf16 v[48:51], v[140:143], v[136:139], v[120:123]
	v_mfma_f32_16x16x32_bf16 v[32:35], v[148:151], v[136:139], v[128:131]
	v_mfma_f32_16x16x32_bf16 v[16:19], v[152:155], v[136:139], v[132:135]
	v_mfma_f32_16x16x32_bf16 v[0:3], v[156:159], v[136:139], v[0:3]
	s_setprio 0
	s_waitcnt vmcnt(0)
	s_cmpk_gt_i32 s1, 0x7f
	s_barrier
	s_cbranch_scc0 .LBB0_1710
	s_add_i32 s0, s24, 0xffffc000
	s_lshr_b32 s0, s0, 8
	v_readlane_b32 s6, v180, 24
	s_add_i32 s6, s0, s6
	s_and_b32 s10, s24, 0x80
	s_lshl_b64 s[8:9], s[6:7], 8
	v_readlane_b32 s36, v182, 19
	s_or_b32 s8, s8, s10
	s_mov_b64 s[10:11], 0
	v_readlane_b32 s37, v182, 20
	s_branch .LBB0_1711
